# cross-tile pipelined prompt loop with the staging writes and their two barriers moved to mid-tile (after the tenth MFMA)
# speedup vs baseline: 1.0063x; 1.0063x over previous
.LBB0_822:
	s_mov_b32 s5, 0
	v_exp_f32_e32 v124, v84
	v_exp_f32_e32 v125, v85
	v_exp_f32_e32 v126, v86
	v_add_f32_e32 v224, v124, v125
	s_waitcnt lgkmcnt(4)
	v_mfma_f32_32x32x16_bf16 v[4:19], v[164:167], v[144:147], v[4:19]
	v_exp_f32_e32 v127, v87
	v_cvt_pk_bf16_f32 v184, v124, v125
	v_mov_b32_e32 v254, v224
	v_exp_f32_e32 v128, v88
	s_waitcnt lgkmcnt(2)
	v_mfma_f32_32x32x16_bf16 v[20:35], v[168:171], v[144:147], v[20:35]
	ds_read_b64_tr_b16 v[176:177], v162 offset:29760
	ds_read_b64_tr_b16 v[178:179], v162 offset:31296
	v_add_f32_e32 v226, v126, v127
	v_exp_f32_e32 v129, v89
	v_cvt_pk_bf16_f32 v185, v126, v127
	v_add_f32_e32 v254, v254, v226
	s_waitcnt lgkmcnt(2)
	v_mfma_f32_32x32x16_bf16 v[4:19], v[172:175], v[140:143], v[4:19]
	ds_read_b64_tr_b16 v[164:165], v162 offset:32768
	ds_read_b64_tr_b16 v[166:167], v162 offset:34304
	v_exp_f32_e32 v130, v90
	v_add_f32_e32 v233, v128, v129
	v_exp_f32_e32 v131, v91
	v_cvt_pk_bf16_f32 v186, v128, v129
	s_waitcnt lgkmcnt(2)
	v_mfma_f32_32x32x16_bf16 v[20:35], v[176:179], v[140:143], v[20:35]
	ds_read_b64_tr_b16 v[168:169], v162 offset:32832
	ds_read_b64_tr_b16 v[170:171], v162 offset:34368
	v_add_f32_e32 v254, v254, v233
	v_exp_f32_e32 v124, v92
	v_add_f32_e32 v224, v130, v131
	v_exp_f32_e32 v125, v93
	s_waitcnt lgkmcnt(2)
	v_mfma_f32_32x32x16_bf16 v[4:19], v[164:167], v[136:139], v[4:19]
	ds_read_b64_tr_b16 v[172:173], v162 offset:35840
	ds_read_b64_tr_b16 v[174:175], v162 offset:37376
	v_cvt_pk_bf16_f32 v187, v130, v131
	v_add_f32_e32 v254, v254, v224
	v_exp_f32_e32 v126, v94
	v_add_f32_e32 v226, v124, v125
	s_waitcnt lgkmcnt(2)
	v_mfma_f32_32x32x16_bf16 v[20:35], v[168:171], v[136:139], v[20:35]
	ds_read_b64_tr_b16 v[176:177], v162 offset:35904
	ds_read_b64_tr_b16 v[178:179], v162 offset:37440
	v_exp_f32_e32 v127, v95
	v_cvt_pk_bf16_f32 v188, v124, v125
	v_add_f32_e32 v254, v254, v226
	v_exp_f32_e32 v128, v96
	s_waitcnt lgkmcnt(2)
	v_mfma_f32_32x32x16_bf16 v[4:19], v[172:175], v[132:135], v[4:19]
	ds_read_b128 v[180:183], v155 offset:0
	ds_read_b128 v[112:115], v155 offset:6656
	v_add_f32_e32 v233, v126, v127
	v_exp_f32_e32 v129, v97
	v_cvt_pk_bf16_f32 v189, v126, v127
	v_add_f32_e32 v254, v254, v233
	s_waitcnt lgkmcnt(2)
	v_mfma_f32_32x32x16_bf16 v[20:35], v[176:179], v[132:135], v[20:35]
	ds_read_b128 v[116:119], v155 offset:32
	ds_read_b128 v[120:123], v155 offset:6688
	v_exp_f32_e32 v130, v98
	v_add_f32_e32 v224, v128, v129
	v_exp_f32_e32 v131, v99
	v_cvt_pk_bf16_f32 v190, v128, v129
	s_waitcnt lgkmcnt(3)
	v_mfma_f32_32x32x16_bf16 v[52:67], v[180:183], v[200:203], v[234:249]
	ds_read_b128 v[180:183], v155 offset:64
	v_add_f32_e32 v254, v254, v224
	v_exp_f32_e32 v124, v36
	v_add_f32_e32 v226, v130, v131
	v_exp_f32_e32 v125, v37
	s_waitcnt lgkmcnt(3)
	v_mfma_f32_32x32x16_bf16 v[68:83], v[112:115], v[200:203], v[234:249]
	s_barrier
	s_waitcnt vmcnt(0)
	ds_write_b128 v157, v[104:107] offset:13312
	ds_write_b64 v158, v[108:109] offset:13440
	ds_write_b128 v151, v[100:103] offset:38912
	buffer_load_dwordx2 v[108:109], v161, s[12:15], s52 offen
	s_add_i32 s3, s53, 0xfe040000
	buffer_load_dwordx4 v[104:107], v150, s[12:15], s3 offen
	buffer_load_dwordx4 v[100:103], v150, s[12:15], s53 offen
	ds_read_b128 v[112:115], v155 offset:6720
	v_cvt_pk_bf16_f32 v191, v130, v131
	v_add_f32_e32 v254, v254, v226
	v_exp_f32_e32 v126, v38
	v_add_f32_e32 v233, v124, v125
	s_waitcnt lgkmcnt(6)
	v_mfma_f32_32x32x16_bf16 v[52:67], v[116:119], v[204:207], v[52:67]
	ds_read_b128 v[116:119], v155 offset:96
	v_exp_f32_e32 v127, v39
	v_cvt_pk_bf16_f32 v192, v124, v125
	v_add_f32_e32 v254, v254, v233
	v_exp_f32_e32 v128, v40
	s_waitcnt lgkmcnt(6)
	v_mfma_f32_32x32x16_bf16 v[68:83], v[120:123], v[204:207], v[68:83]
	ds_read_b128 v[120:123], v155 offset:6752
	v_add_f32_e32 v224, v126, v127
	v_exp_f32_e32 v129, v41
	v_cvt_pk_bf16_f32 v193, v126, v127
	v_add_f32_e32 v254, v254, v224
	s_waitcnt lgkmcnt(6)
	v_mfma_f32_32x32x16_bf16 v[52:67], v[180:183], v[208:211], v[52:67]
	ds_read_b128 v[180:183], v155 offset:128
	v_exp_f32_e32 v130, v42
	v_add_f32_e32 v226, v128, v129
	v_exp_f32_e32 v131, v43
	v_cvt_pk_bf16_f32 v194, v128, v129
	s_waitcnt lgkmcnt(3)
	v_mfma_f32_32x32x16_bf16 v[68:83], v[112:115], v[208:211], v[68:83]
	s_barrier
	ds_read_b128 v[112:115], v155 offset:6784
	v_add_f32_e32 v254, v254, v226
	v_exp_f32_e32 v124, v44
	v_add_f32_e32 v233, v130, v131
	v_exp_f32_e32 v125, v45
	s_waitcnt lgkmcnt(3)
	v_mfma_f32_32x32x16_bf16 v[52:67], v[116:119], v[212:215], v[52:67]
	ds_read_b128 v[116:119], v155 offset:160
	v_cvt_pk_bf16_f32 v195, v130, v131
	v_add_f32_e32 v254, v254, v233
	v_exp_f32_e32 v126, v46
	v_add_f32_e32 v224, v124, v125
	s_waitcnt lgkmcnt(3)
	v_mfma_f32_32x32x16_bf16 v[68:83], v[120:123], v[212:215], v[68:83]
	ds_read_b128 v[120:123], v155 offset:6816
	v_exp_f32_e32 v127, v47
	v_cvt_pk_bf16_f32 v196, v124, v125
	v_add_f32_e32 v254, v254, v224
	v_exp_f32_e32 v128, v48
	s_waitcnt lgkmcnt(3)
	v_mfma_f32_32x32x16_bf16 v[52:67], v[180:183], v[216:219], v[52:67]
	v_add_f32_e32 v226, v126, v127
	v_exp_f32_e32 v129, v49
	v_cvt_pk_bf16_f32 v197, v126, v127
	v_add_f32_e32 v254, v254, v226
	s_waitcnt lgkmcnt(2)
	v_mfma_f32_32x32x16_bf16 v[68:83], v[112:115], v[216:219], v[68:83]
	v_exp_f32_e32 v130, v50
	v_add_f32_e32 v233, v128, v129
	v_exp_f32_e32 v131, v51
	v_cvt_pk_bf16_f32 v198, v128, v129
	s_waitcnt lgkmcnt(1)
	v_mfma_f32_32x32x16_bf16 v[52:67], v[116:119], v[250:253], v[52:67]
	v_add_f32_e32 v254, v254, v233
	v_add_f32_e32 v224, v130, v131
	v_cvt_pk_bf16_f32 v199, v130, v131
	v_add_f32_e32 v254, v254, v224
	s_waitcnt lgkmcnt(0)
	v_mfma_f32_32x32x16_bf16 v[68:83], v[120:123], v[250:253], v[68:83]
	v_cmp_lt_f32_e32 vcc, 0x43800000, v254
	s_cbranch_vccnz .LpfU_s0

.LpfU_nr0:
	s_mov_b32 s5, 0
	v_exp_f32_e32 v124, v52
	v_exp_f32_e32 v125, v53
	v_exp_f32_e32 v126, v54
	v_add_f32_e32 v224, v124, v125
	s_waitcnt lgkmcnt(4)
	v_mfma_f32_32x32x16_bf16 v[4:19], v[164:167], v[184:187], v[4:19]
	v_exp_f32_e32 v127, v55
	v_cvt_pk_bf16_f32 v144, v124, v125
	v_mov_b32_e32 v254, v224
	v_exp_f32_e32 v128, v56
	s_waitcnt lgkmcnt(2)
	v_mfma_f32_32x32x16_bf16 v[20:35], v[168:171], v[184:187], v[20:35]
	ds_read_b64_tr_b16 v[176:177], v162 offset:42048
	ds_read_b64_tr_b16 v[178:179], v162 offset:43584
	v_add_f32_e32 v226, v126, v127
	v_exp_f32_e32 v129, v57
	v_cvt_pk_bf16_f32 v145, v126, v127
	v_add_f32_e32 v254, v254, v226
	s_waitcnt lgkmcnt(2)
	v_mfma_f32_32x32x16_bf16 v[4:19], v[172:175], v[188:191], v[4:19]
	ds_read_b64_tr_b16 v[164:165], v162 offset:45056
	ds_read_b64_tr_b16 v[166:167], v162 offset:46592
	v_exp_f32_e32 v130, v58
	v_add_f32_e32 v233, v128, v129
	v_exp_f32_e32 v131, v59
	v_cvt_pk_bf16_f32 v146, v128, v129
	s_waitcnt lgkmcnt(2)
	v_mfma_f32_32x32x16_bf16 v[20:35], v[176:179], v[188:191], v[20:35]
	ds_read_b64_tr_b16 v[168:169], v162 offset:45120
	ds_read_b64_tr_b16 v[170:171], v162 offset:46656
	v_add_f32_e32 v254, v254, v233
	v_exp_f32_e32 v124, v60
	v_add_f32_e32 v224, v130, v131
	v_exp_f32_e32 v125, v61
	s_waitcnt lgkmcnt(2)
	v_mfma_f32_32x32x16_bf16 v[4:19], v[164:167], v[192:195], v[4:19]
	ds_read_b64_tr_b16 v[172:173], v162 offset:48128
	ds_read_b64_tr_b16 v[174:175], v162 offset:49664
	v_cvt_pk_bf16_f32 v147, v130, v131
	v_add_f32_e32 v254, v254, v224
	v_exp_f32_e32 v126, v62
	v_add_f32_e32 v226, v124, v125
	s_waitcnt lgkmcnt(2)
	v_mfma_f32_32x32x16_bf16 v[20:35], v[168:171], v[192:195], v[20:35]
	ds_read_b64_tr_b16 v[176:177], v162 offset:48192
	ds_read_b64_tr_b16 v[178:179], v162 offset:49728
	v_exp_f32_e32 v127, v63
	v_cvt_pk_bf16_f32 v140, v124, v125
	v_add_f32_e32 v254, v254, v226
	v_exp_f32_e32 v128, v64
	s_waitcnt lgkmcnt(2)
	v_mfma_f32_32x32x16_bf16 v[4:19], v[172:175], v[196:199], v[4:19]
	ds_read_b128 v[180:183], v155 offset:13312
	ds_read_b128 v[112:115], v155 offset:19968
	v_add_f32_e32 v233, v126, v127
	v_exp_f32_e32 v129, v65
	v_cvt_pk_bf16_f32 v141, v126, v127
	v_add_f32_e32 v254, v254, v233
	s_waitcnt lgkmcnt(2)
	v_mfma_f32_32x32x16_bf16 v[20:35], v[176:179], v[196:199], v[20:35]
	ds_read_b128 v[116:119], v155 offset:13344
	ds_read_b128 v[120:123], v155 offset:20000
	v_exp_f32_e32 v130, v66
	v_add_f32_e32 v224, v128, v129
	v_exp_f32_e32 v131, v67
	v_cvt_pk_bf16_f32 v142, v128, v129
	s_waitcnt lgkmcnt(3)
	v_mfma_f32_32x32x16_bf16 v[84:99], v[180:183], v[200:203], v[234:249]
	ds_read_b128 v[180:183], v155 offset:13376
	v_add_f32_e32 v254, v254, v224
	v_exp_f32_e32 v124, v68
	v_add_f32_e32 v226, v130, v131
	v_exp_f32_e32 v125, v69
	s_waitcnt lgkmcnt(3)
	v_mfma_f32_32x32x16_bf16 v[36:51], v[112:115], v[200:203], v[234:249]
	s_barrier
	s_waitcnt vmcnt(0)
	ds_write_b128 v157, v[104:107]
	ds_write_b64 v158, v[108:109] offset:128
	ds_write_b128 v151, v[100:103] offset:26624
	s_add_i32 s2, s51, 2
	s_cmp_lt_i32 s2, s50
	s_cbranch_scc0 .LpfU_nl
	s_add_i32 s2, s52, 0x1000
	buffer_load_dwordx2 v[108:109], v161, s[12:15], s2 offen
	s_add_i32 s3, s53, 0xfe060000
	buffer_load_dwordx4 v[104:107], v150, s[12:15], s3 offen
	s_add_i32 s4, s53, 0x20000
	buffer_load_dwordx4 v[100:103], v150, s[12:15], s4 offen
.LpfU_nl:
	ds_read_b128 v[112:115], v155 offset:20032
	v_cvt_pk_bf16_f32 v143, v130, v131
	v_add_f32_e32 v254, v254, v226
	v_exp_f32_e32 v126, v70
	v_add_f32_e32 v233, v124, v125
	s_waitcnt lgkmcnt(6)
	v_mfma_f32_32x32x16_bf16 v[84:99], v[116:119], v[204:207], v[84:99]
	ds_read_b128 v[116:119], v155 offset:13408
	v_exp_f32_e32 v127, v71
	v_cvt_pk_bf16_f32 v136, v124, v125
	v_add_f32_e32 v254, v254, v233
	v_exp_f32_e32 v128, v72
	s_waitcnt lgkmcnt(6)
	v_mfma_f32_32x32x16_bf16 v[36:51], v[120:123], v[204:207], v[36:51]
	ds_read_b128 v[120:123], v155 offset:20064
	v_add_f32_e32 v224, v126, v127
	v_exp_f32_e32 v129, v73
	v_cvt_pk_bf16_f32 v137, v126, v127
	v_add_f32_e32 v254, v254, v224
	s_waitcnt lgkmcnt(6)
	v_mfma_f32_32x32x16_bf16 v[84:99], v[180:183], v[208:211], v[84:99]
	ds_read_b128 v[180:183], v155 offset:13440
	v_exp_f32_e32 v130, v74
	v_add_f32_e32 v226, v128, v129
	v_exp_f32_e32 v131, v75
	v_cvt_pk_bf16_f32 v138, v128, v129
	s_waitcnt lgkmcnt(3)
	v_mfma_f32_32x32x16_bf16 v[36:51], v[112:115], v[208:211], v[36:51]
	s_barrier
	ds_read_b128 v[112:115], v155 offset:20096
	v_add_f32_e32 v254, v254, v226
	v_exp_f32_e32 v124, v76
	v_add_f32_e32 v233, v130, v131
	v_exp_f32_e32 v125, v77
	s_waitcnt lgkmcnt(3)
	v_mfma_f32_32x32x16_bf16 v[84:99], v[116:119], v[212:215], v[84:99]
	ds_read_b128 v[116:119], v155 offset:13472
	v_cvt_pk_bf16_f32 v139, v130, v131
	v_add_f32_e32 v254, v254, v233
	v_exp_f32_e32 v126, v78
	v_add_f32_e32 v224, v124, v125
	s_waitcnt lgkmcnt(3)
	v_mfma_f32_32x32x16_bf16 v[36:51], v[120:123], v[212:215], v[36:51]
	ds_read_b128 v[120:123], v155 offset:20128
	v_exp_f32_e32 v127, v79
	v_cvt_pk_bf16_f32 v132, v124, v125
	v_add_f32_e32 v254, v254, v224
	v_exp_f32_e32 v128, v80
	s_waitcnt lgkmcnt(3)
	v_mfma_f32_32x32x16_bf16 v[84:99], v[180:183], v[216:219], v[84:99]
	v_add_f32_e32 v226, v126, v127
	v_exp_f32_e32 v129, v81
	v_cvt_pk_bf16_f32 v133, v126, v127
	v_add_f32_e32 v254, v254, v226
	s_waitcnt lgkmcnt(2)
	v_mfma_f32_32x32x16_bf16 v[36:51], v[112:115], v[216:219], v[36:51]
	v_exp_f32_e32 v130, v82
	v_add_f32_e32 v233, v128, v129
	v_exp_f32_e32 v131, v83
	v_cvt_pk_bf16_f32 v134, v128, v129
	s_waitcnt lgkmcnt(1)
	v_mfma_f32_32x32x16_bf16 v[84:99], v[116:119], v[250:253], v[84:99]
	v_add_f32_e32 v254, v254, v233
	v_add_f32_e32 v224, v130, v131
	v_cvt_pk_bf16_f32 v135, v130, v131
	v_add_f32_e32 v254, v254, v224
	s_waitcnt lgkmcnt(0)
	v_mfma_f32_32x32x16_bf16 v[36:51], v[120:123], v[250:253], v[36:51]
	v_cmp_lt_f32_e32 vcc, 0x43800000, v254
	s_cbranch_vccnz .LpfU_s1
